# attention loop second half: lumped finishSM VALU (exp, row-sum chain, bf16 packs) spread over the empty QK^T MFMA gaps via free temporaries v[224:227]; first PV group's V reads issued right after the
# speedup vs baseline: 1.0057x; 1.0001x over previous
.LBB0_457:
	v_cndmask_b32_e64 v221, v164, v168, s[42:43]
	v_mul_f32_e32 v222, 0xbe0293ee, v221
	v_fmamk_f32 v82, v82, 0x3e0293ee, v222
	v_fmamk_f32 v83, v83, 0x3e0293ee, v222
	v_fmamk_f32 v84, v84, 0x3e0293ee, v222
	v_fmamk_f32 v85, v85, 0x3e0293ee, v222
	v_fmamk_f32 v86, v86, 0x3e0293ee, v222
	v_fmamk_f32 v87, v87, 0x3e0293ee, v222
	v_fmamk_f32 v88, v88, 0x3e0293ee, v222
	v_fmamk_f32 v89, v89, 0x3e0293ee, v222
	v_fmamk_f32 v90, v90, 0x3e0293ee, v222
	v_fmamk_f32 v91, v91, 0x3e0293ee, v222
	v_fmamk_f32 v92, v92, 0x3e0293ee, v222
	v_fmamk_f32 v93, v93, 0x3e0293ee, v222
	v_fmamk_f32 v94, v94, 0x3e0293ee, v222
	v_fmamk_f32 v95, v95, 0x3e0293ee, v222
	v_fmamk_f32 v96, v96, 0x3e0293ee, v222
	v_fmamk_f32 v97, v97, 0x3e0293ee, v222
	v_exp_f32_e32 v164, v82
	v_exp_f32_e32 v179, v83
	v_exp_f32_e32 v165, v84
	v_exp_f32_e32 v178, v85
	v_exp_f32_e32 v166, v86
	v_exp_f32_e32 v177, v87
	v_exp_f32_e32 v167, v88
	v_exp_f32_e32 v176, v89
	v_exp_f32_e32 v168, v90
	v_exp_f32_e32 v175, v91
	v_exp_f32_e32 v169, v92
	v_exp_f32_e32 v174, v93
	v_exp_f32_e32 v170, v94
	v_exp_f32_e32 v173, v95
	v_exp_f32_e32 v171, v96
	v_exp_f32_e32 v172, v97
	v_fmamk_f32 v238, v66, 0x3e0293ee, v222
	v_fmamk_f32 v239, v67, 0x3e0293ee, v222
	v_fmamk_f32 v240, v68, 0x3e0293ee, v222
	v_fmamk_f32 v241, v69, 0x3e0293ee, v222
	v_fmamk_f32 v242, v70, 0x3e0293ee, v222
	v_fmamk_f32 v231, v71, 0x3e0293ee, v222
	v_fmamk_f32 v232, v72, 0x3e0293ee, v222
	v_fmamk_f32 v233, v73, 0x3e0293ee, v222
	v_fmamk_f32 v234, v74, 0x3e0293ee, v222
	v_fmamk_f32 v235, v75, 0x3e0293ee, v222
	v_fmamk_f32 v236, v76, 0x3e0293ee, v222
	v_fmamk_f32 v237, v77, 0x3e0293ee, v222
	v_fmamk_f32 v223, v78, 0x3e0293ee, v222
	v_fmamk_f32 v243, v79, 0x3e0293ee, v222
	v_fmamk_f32 v244, v80, 0x3e0293ee, v222
	v_fmac_f32_e32 v222, 0x3e0293ee, v81
	s_waitcnt lgkmcnt(0)
	s_barrier
	ds_read_b128 v[66:69], v209 offset:32768
	ds_read_b128 v[70:73], v209 offset:40960
	ds_read_b128 v[246:249], v214 offset:32768
	ds_read_b128 v[196:199], v214 offset:40960
	ds_read_b128 v[200:203], v213 offset:32768
	ds_read_b128 v[204:207], v213 offset:40960
	v_exp_f32_e32 v231, v231
	v_exp_f32_e32 v232, v232
	s_waitcnt lgkmcnt(5)
	v_mfma_f32_32x32x16_bf16 v[82:97], v[66:69], v[120:123], 0
	v_exp_f32_e32 v233, v233
	v_exp_f32_e32 v234, v234
	v_exp_f32_e32 v235, v235
	v_exp_f32_e32 v236, v236
	v_exp_f32_e32 v237, v237
	s_waitcnt lgkmcnt(4)
	v_mfma_f32_32x32x16_bf16 v[66:81], v[70:73], v[120:123], 0
	s_waitcnt lgkmcnt(3)
	v_mfma_f32_32x32x16_bf16 v[82:97], v[246:249], v[112:115], v[82:97]
	v_exp_f32_e32 v224, v238
	v_exp_f32_e32 v238, v242
	v_exp_f32_e32 v242, v222
	v_add_f32_e32 v222, 0, v164
	v_add_f32_e32 v222, v179, v222
	s_waitcnt lgkmcnt(2)
	v_mfma_f32_32x32x16_bf16 v[66:81], v[196:199], v[112:115], v[66:81]
	ds_read_b128 v[196:199], v212 offset:32768
	ds_read_b128 v[246:249], v212 offset:40960
	v_add_f32_e32 v222, v165, v222
	v_add_f32_e32 v222, v178, v222
	v_add_f32_e32 v222, v166, v222
	v_add_f32_e32 v222, v177, v222
	v_add_f32_e32 v222, v167, v222
	s_waitcnt lgkmcnt(3)
	v_mfma_f32_32x32x16_bf16 v[82:97], v[200:203], v[128:131], v[82:97]
	v_add_f32_e32 v222, v176, v222
	v_add_f32_e32 v222, v168, v222
	v_add_f32_e32 v222, v175, v222
	v_add_f32_e32 v222, v169, v222
	v_add_f32_e32 v222, v174, v222
	s_waitcnt lgkmcnt(2)
	v_mfma_f32_32x32x16_bf16 v[66:81], v[204:207], v[128:131], v[66:81]
	ds_read_b128 v[200:203], v211 offset:32768
	ds_read_b128 v[204:207], v211 offset:40960
	v_add_f32_e32 v222, v170, v222
	v_exp_f32_e32 v225, v239
	v_add_f32_e32 v222, v173, v222
	v_exp_f32_e32 v226, v240
	v_add_f32_e32 v222, v171, v222
	s_waitcnt lgkmcnt(3)
	v_mfma_f32_32x32x16_bf16 v[82:97], v[196:199], v[124:127], v[82:97]
	v_exp_f32_e32 v227, v241
	v_add_f32_e32 v222, v172, v222
	v_add_f32_e32 v222, v224, v222
	v_add_f32_e32 v222, v225, v222
	v_add_f32_e32 v222, v226, v222
	s_waitcnt lgkmcnt(2)
	v_mfma_f32_32x32x16_bf16 v[66:81], v[246:249], v[124:127], v[66:81]
	ds_read_b128 v[196:199], v210 offset:32768
	ds_read_b128 v[246:249], v210 offset:40960
	v_add_f32_e32 v222, v227, v222
	v_add_f32_e32 v222, v238, v222
	v_add_f32_e32 v222, v231, v222
	v_add_f32_e32 v222, v232, v222
	v_add_f32_e32 v222, v233, v222
	s_waitcnt lgkmcnt(3)
	v_mfma_f32_32x32x16_bf16 v[82:97], v[200:203], v[116:119], v[82:97]
	v_exp_f32_e32 v239, v223
	v_add_f32_e32 v222, v234, v222
	v_exp_f32_e32 v240, v243
	v_add_f32_e32 v222, v235, v222
	s_waitcnt lgkmcnt(2)
	v_mfma_f32_32x32x16_bf16 v[66:81], v[204:207], v[116:119], v[66:81]
	ds_read_b128 v[200:203], v216 offset:32768
	ds_read_b128 v[204:207], v216 offset:40960
	v_exp_f32_e32 v241, v244
	v_add_f32_e32 v222, v236, v222
	v_add_f32_e32 v222, v237, v222
	v_add_f32_e32 v222, v239, v222
	s_waitcnt lgkmcnt(3)
	v_mfma_f32_32x32x16_bf16 v[82:97], v[196:199], v[108:111], v[82:97]
	v_add_f32_e32 v222, v240, v222
	v_add_f32_e32 v222, v241, v222
	v_add_f32_e32 v222, v242, v222
	v_mov_b32_e32 v223, v222
	s_waitcnt lgkmcnt(2)
	v_mfma_f32_32x32x16_bf16 v[66:81], v[246:249], v[108:111], v[66:81]
	ds_read_b128 v[196:199], v215 offset:32768
	ds_read_b128 v[246:249], v215 offset:40960
	v_cvt_pk_bf16_f32 v164, v164, v179
	v_cvt_pk_bf16_f32 v165, v165, v178
	v_cvt_pk_bf16_f32 v166, v166, v177
	v_cvt_pk_bf16_f32 v167, v167, v176
	s_waitcnt lgkmcnt(3)
	v_mfma_f32_32x32x16_bf16 v[82:97], v[200:203], v[104:107], v[82:97]
	v_cvt_pk_bf16_f32 v168, v168, v175
	v_cvt_pk_bf16_f32 v169, v169, v174
	v_cvt_pk_bf16_f32 v170, v170, v173
	v_cvt_pk_bf16_f32 v171, v171, v172
	s_waitcnt lgkmcnt(2)
	v_mfma_f32_32x32x16_bf16 v[66:81], v[204:207], v[104:107], v[66:81]
	v_cvt_pk_bf16_f32 v172, v224, v225
	v_cvt_pk_bf16_f32 v173, v226, v227
	v_cvt_pk_bf16_f32 v174, v238, v231
	v_cvt_pk_bf16_f32 v175, v232, v233
	s_waitcnt lgkmcnt(1)
	v_mfma_f32_32x32x16_bf16 v[82:97], v[196:199], v[100:103], v[82:97]
	v_cvt_pk_bf16_f32 v176, v234, v235
	v_cvt_pk_bf16_f32 v177, v236, v237
	v_cvt_pk_bf16_f32 v178, v239, v240
	v_cvt_pk_bf16_f32 v179, v241, v242
	s_waitcnt lgkmcnt(0)
	v_mfma_f32_32x32x16_bf16 v[66:81], v[246:249], v[100:103], v[66:81]
	ds_read_b64_tr_b16 v[196:197], v191 offset:0
	ds_read_b64_tr_b16 v[198:199], v191 offset:0x800
	ds_read_b64_tr_b16 v[232:233], v191 offset:0x1000
	ds_read_b64_tr_b16 v[234:235], v191 offset:0x1800
	ds_read_b64_tr_b16 v[236:237], v191 offset:0x2000
	ds_read_b64_tr_b16 v[238:239], v191 offset:0x2800
	ds_read_b64_tr_b16 v[240:241], v191 offset:0x3000
	ds_read_b64_tr_b16 v[242:243], v191 offset:0x3800
	s_nop 1
	v_permlane32_swap_b32_e32 v222, v223
	v_permlane32_swap_b32_e32 v164, v166
	v_permlane32_swap_b32_e32 v165, v167
	v_permlane32_swap_b32_e32 v168, v170
	v_permlane32_swap_b32_e32 v169, v171
	v_permlane32_swap_b32_e32 v172, v174
	v_permlane32_swap_b32_e32 v173, v175
	v_permlane32_swap_b32_e32 v176, v178
	v_permlane32_swap_b32_e32 v177, v179
	s_cmp_gt_u32 s6, 64
	s_cselect_b64 s[4:5], -1, 0
	s_and_b64 vcc, exec, s[4:5]
	s_cbranch_vccnz .LBB0_459
	v_add_co_u32_e32 v132, vcc, 0xffffc000, v180
	s_nop 1
	v_addc_co_u32_e32 v133, vcc, -1, v181, vcc
	v_add_co_u32_e32 v136, vcc, 0xff77c000, v180
	s_nop 1
	v_addc_co_u32_e32 v137, vcc, -1, v181, vcc
	v_add_co_u32_e32 v144, vcc, 0xff780000, v180
	global_load_dwordx4 v[132:135], v[132:133], off
	s_nop 0
	global_load_dwordx4 v[136:139], v[136:137], off
	v_addc_co_u32_e32 v145, vcc, -1, v181, vcc
	global_load_dwordx4 v[140:143], v[180:181], off
	s_nop 0
	global_load_dwordx4 v[144:147], v[144:145], off
.LBB0_459:
	s_waitcnt lgkmcnt(0)
	s_nop 0
	v_mfma_f32_32x32x16_bf16 v[2:17], v[164:167], v[196:199], v[2:17]
	ds_read_b64_tr_b16 v[196:197], v191 offset:0x200
	ds_read_b64_tr_b16 v[198:199], v191 offset:0xa00
	v_mfma_f32_32x32x16_bf16 v[2:17], v[168:171], v[232:235], v[2:17]
	ds_read_b64_tr_b16 v[232:233], v191 offset:0x1200
	ds_read_b64_tr_b16 v[234:235], v191 offset:0x1a00
	v_mfma_f32_32x32x16_bf16 v[2:17], v[172:175], v[236:239], v[2:17]
	ds_read_b64_tr_b16 v[236:237], v191 offset:0x2200
	ds_read_b64_tr_b16 v[238:239], v191 offset:0x2a00
	v_mfma_f32_32x32x16_bf16 v[2:17], v[176:179], v[240:243], v[2:17]
	ds_read_b64_tr_b16 v[240:241], v191 offset:0x3200
	ds_read_b64_tr_b16 v[242:243], v191 offset:0x3a00
	s_waitcnt lgkmcnt(0)
	v_mfma_f32_32x32x16_bf16 v[50:65], v[164:167], v[196:199], v[50:65]
	ds_read_b64_tr_b16 v[196:197], v191 offset:0x400
	ds_read_b64_tr_b16 v[198:199], v191 offset:0xc00
	v_mfma_f32_32x32x16_bf16 v[50:65], v[168:171], v[232:235], v[50:65]
	ds_read_b64_tr_b16 v[232:233], v191 offset:0x1400
	ds_read_b64_tr_b16 v[234:235], v191 offset:0x1c00
	v_mfma_f32_32x32x16_bf16 v[50:65], v[172:175], v[236:239], v[50:65]
	ds_read_b64_tr_b16 v[236:237], v191 offset:0x2400
	ds_read_b64_tr_b16 v[238:239], v191 offset:0x2c00
	v_mfma_f32_32x32x16_bf16 v[50:65], v[176:179], v[240:243], v[50:65]
	ds_read_b64_tr_b16 v[240:241], v191 offset:0x3400
	ds_read_b64_tr_b16 v[242:243], v191 offset:0x3c00
	s_waitcnt lgkmcnt(0)
	v_mfma_f32_32x32x16_bf16 v[34:49], v[164:167], v[196:199], v[34:49]
	ds_read_b64_tr_b16 v[196:197], v191 offset:0x600
	ds_read_b64_tr_b16 v[198:199], v191 offset:0xe00
	v_mfma_f32_32x32x16_bf16 v[34:49], v[168:171], v[232:235], v[34:49]
	ds_read_b64_tr_b16 v[232:233], v191 offset:0x1600
	ds_read_b64_tr_b16 v[234:235], v191 offset:0x1e00
	v_mfma_f32_32x32x16_bf16 v[34:49], v[172:175], v[236:239], v[34:49]
	ds_read_b64_tr_b16 v[236:237], v191 offset:0x2600
	ds_read_b64_tr_b16 v[238:239], v191 offset:0x2e00
	v_mfma_f32_32x32x16_bf16 v[34:49], v[176:179], v[240:243], v[34:49]
	ds_read_b64_tr_b16 v[240:241], v191 offset:0x3600
	ds_read_b64_tr_b16 v[242:243], v191 offset:0x3e00
	s_waitcnt lgkmcnt(0)
	v_mfma_f32_32x32x16_bf16 v[18:33], v[164:167], v[196:199], v[18:33]
	v_max_f32_e32 v164, v83, v83
	v_max_f32_e32 v165, v82, v82
	v_max_f32_e32 v164, v165, v164
	v_max3_f32 v164, v164, v84, v85
	v_max3_f32 v164, v164, v86, v87
	v_max3_f32 v164, v164, v88, v89
	v_max3_f32 v164, v164, v90, v91
	v_max3_f32 v164, v164, v92, v93
	v_max3_f32 v164, v164, v94, v95
	v_mfma_f32_32x32x16_bf16 v[18:33], v[168:171], v[232:235], v[18:33]
	v_max3_f32 v164, v164, v96, v97
	v_max3_f32 v164, v164, v66, v67
	v_max3_f32 v164, v164, v68, v69
	v_max3_f32 v164, v164, v70, v71
	v_max3_f32 v164, v164, v72, v73
	v_max3_f32 v164, v164, v74, v75
	v_max3_f32 v164, v164, v76, v77
	v_max3_f32 v164, v164, v78, v79
	v_mfma_f32_32x32x16_bf16 v[18:33], v[172:175], v[236:239], v[18:33]
	v_max3_f32 v164, v164, v80, v81
	v_mov_b32_e32 v165, v164
	s_nop 1
	v_permlane32_swap_b32_e32 v164, v165
	v_max_f32_e32 v165, v165, v165
	v_max_f32_e32 v164, v164, v164
	v_max_f32_e32 v164, v164, v165
	v_sub_f32_e32 v165, v164, v221
	v_cmp_ge_f32_e32 vcc, s0, v165
	v_max_f32_e32 v165, v221, v221
	v_max_f32_e32 v165, v165, v164
	v_mfma_f32_32x32x16_bf16 v[18:33], v[176:179], v[240:243], v[18:33]
	v_sub_f32_e32 v164, v221, v165
	v_mul_f32_e32 v164, 0x3e0293ee, v164
	v_exp_f32_e32 v164, v164
	s_cmp_eq_u64 vcc, exec
	s_cselect_b64 s[42:43], -1, 0
	s_barrier
	s_waitcnt vmcnt(4)
	v_cndmask_b32_e64 v164, v164, 1.0, s[42:43]
	v_cmp_gt_f32_e32 vcc, 1.0, v164
	s_waitcnt vmcnt(3)
	ds_write_b128 v195, v[148:151] offset:16384
	s_waitcnt vmcnt(2)
	ds_write_b128 v208, v[152:155] offset:16384
	s_waitcnt vmcnt(1)
	ds_write_b128 v193, v[156:159] offset:49152
	s_waitcnt vmcnt(0)
	ds_write_b128 v194, v[160:163] offset:49152
	s_cbranch_vccz .LBB0_463
	s_and_saveexec_b64 s[20:21], s[40:41]
	ds_write_b32 v189, v164 offset:128
	s_or_b64 exec, exec, s[20:21]
	s_waitcnt lgkmcnt(0)
	v_add_u32_e32 v160, v188, v98
	ds_read_b128 v[148:151], v160 offset:224
	ds_read_b128 v[152:155], v160 offset:192
	ds_read_b128 v[156:159], v160 offset:160
	ds_read_b128 v[160:163], v160 offset:128
	s_waitcnt lgkmcnt(3)
	v_pk_mul_f32 v[14:15], v[14:15], v[148:149]
	s_waitcnt lgkmcnt(2)
	v_pk_mul_f32 v[10:11], v[10:11], v[152:153]
	s_waitcnt lgkmcnt(1)
	v_pk_mul_f32 v[6:7], v[6:7], v[156:157]
	v_pk_mul_f32 v[16:17], v[16:17], v[150:151]
	v_pk_mul_f32 v[12:13], v[12:13], v[154:155]
	v_pk_mul_f32 v[8:9], v[8:9], v[158:159]
	s_waitcnt lgkmcnt(0)
	v_pk_mul_f32 v[4:5], v[4:5], v[162:163]
	v_pk_mul_f32 v[2:3], v[2:3], v[160:161]
	v_pk_mul_f32 v[62:63], v[62:63], v[148:149]
	v_pk_mul_f32 v[58:59], v[58:59], v[152:153]
	v_pk_mul_f32 v[54:55], v[54:55], v[156:157]
	v_pk_mul_f32 v[64:65], v[64:65], v[150:151]
	v_pk_mul_f32 v[60:61], v[60:61], v[154:155]
	v_pk_mul_f32 v[56:57], v[56:57], v[158:159]
	v_pk_mul_f32 v[52:53], v[52:53], v[162:163]
	v_pk_mul_f32 v[50:51], v[50:51], v[160:161]
	v_pk_mul_f32 v[46:47], v[46:47], v[148:149]
	v_pk_mul_f32 v[42:43], v[42:43], v[152:153]
	v_pk_mul_f32 v[38:39], v[38:39], v[156:157]
	v_pk_mul_f32 v[48:49], v[48:49], v[150:151]
	v_pk_mul_f32 v[44:45], v[44:45], v[154:155]
	v_pk_mul_f32 v[40:41], v[40:41], v[158:159]
	v_pk_mul_f32 v[36:37], v[36:37], v[162:163]
	v_pk_mul_f32 v[34:35], v[34:35], v[160:161]
	v_pk_mul_f32 v[30:31], v[30:31], v[148:149]
	v_pk_mul_f32 v[26:27], v[26:27], v[152:153]
	v_pk_mul_f32 v[22:23], v[22:23], v[156:157]
	v_pk_mul_f32 v[32:33], v[32:33], v[150:151]
	v_pk_mul_f32 v[28:29], v[28:29], v[154:155]
	v_pk_mul_f32 v[24:25], v[24:25], v[158:159]
	v_pk_mul_f32 v[20:21], v[20:21], v[162:163]
	v_pk_mul_f32 v[18:19], v[18:19], v[160:161]

.LBB0_471:
	v_mov_b32_e32 v224, 0x358637bd
	v_mov_b32_e32 v225, 0x260
	v_mov_b32_e32 v226, 1
	v_mov_b32_e32 v227, 0x2800
	v_mov_b64_e32 v[200:201], 0x100
	v_mov_b64_e32 v[202:203], 0xff
	v_mov_b64_e32 v[204:205], 0x80
	v_mov_b64_e32 v[206:207], 0x7f
	v_readlane_b32 s6, v253, 4
	s_mov_b64 s[4:5], s[96:97]
	v_mov_b32_e32 v10, v0
	v_readlane_b32 s7, v253, 5
	s_andn2_b64 vcc, exec, s[6:7]
	v_readfirstlane_b32 s10, v10
	s_cbranch_vccnz .LBB0_491
	v_lshlrev_b32_e32 v2, 4, v10
	v_add_u32_e32 v3, 0x2000, v2
	v_ashrrev_i32_e32 v4, 31, v3
	v_lshrrev_b32_e32 v4, 22, v4
	v_add_u32_e32 v4, v3, v4
	v_ashrrev_i32_e32 v4, 10, v4
	v_mul_i32_i24_e32 v5, 0x400, v4
	v_sub_u32_e32 v3, v3, v5
	v_lshrrev_b32_e32 v5, 4, v3
	v_bitop3_b32 v3, v5, v3, 32 bitop3:0x6c
	v_ashrrev_i32_e32 v5, 31, v3
	v_lshrrev_b32_e32 v5, 26, v5
	v_add_u32_e32 v5, v3, v5
	v_lshlrev_b32_e32 v7, 3, v4
	v_ashrrev_i32_e32 v6, 6, v5
	v_and_b32_e32 v7, -16, v7
	v_and_b32_e32 v5, 0xc0, v5
	v_add_u32_e32 v7, v6, v7
	v_sub_u32_e32 v3, v3, v5
	s_load_dwordx2 s[20:21], s[4:5], 0xb8
	v_and_b32_e32 v6, 3, v6
	s_mov_b32 s4, 0x7fffe0
	v_lshrrev_b32_e32 v8, 2, v7
	v_lshlrev_b32_e32 v9, 1, v7
	v_lshlrev_b32_e32 v4, 5, v4
	v_ashrrev_i16_sdwa v3, v226, sext(v3) dst_sel:DWORD dst_unused:UNUSED_PAD src0_sel:DWORD src1_sel:BYTE_0
	v_and_or_b32 v6, v7, s4, v6
	v_and_b32_e32 v8, 4, v8
	v_and_b32_e32 v9, 24, v9
	v_and_b32_e32 v4, 32, v4
	v_bfe_i32 v3, v3, 0, 16
	v_or3_b32 v6, v6, v8, v9
	v_add_lshl_u32 v3, v4, v3, 1
	v_lshl_add_u32 v132, v6, 9, v3
	v_lshl_add_u32 v134, v7, 9, v3
	v_bfe_i32 v3, v10, 27, 1
	v_lshrrev_b32_e32 v3, 22, v3
	v_add_u32_e32 v3, v2, v3
	v_and_b32_e32 v3, 0xfffffc00, v3
	v_sub_u32_e32 v2, v2, v3
	v_lshrrev_b32_e32 v3, 4, v2
	v_ashrrev_i32_e32 v5, 31, v10
	v_bitop3_b32 v2, v3, v2, 32 bitop3:0x6c
	v_lshrrev_b32_e32 v5, 26, v5
	v_ashrrev_i32_e32 v3, 31, v2
	v_add_u32_e32 v5, v10, v5
	s_waitcnt lgkmcnt(0)
	s_add_u32 s6, s20, 0x18100000
	v_lshrrev_b32_e32 v3, 26, v3
	v_ashrrev_i32_e32 v5, 6, v5
	s_addc_u32 s7, s21, 0
	v_add_u32_e32 v3, v2, v3
	v_lshlrev_b32_e32 v6, 3, v5
	s_add_u32 s8, s20, 0x31d24000
	v_ashrrev_i32_e32 v4, 6, v3
	v_and_b32_e32 v6, -16, v6
	v_and_b32_e32 v3, 0xc0, v3
	s_addc_u32 s9, s21, 0
	s_ashr_i32 s36, s10, 6
	v_add_u32_e32 v6, v4, v6
	v_and_b32_e32 v4, 3, v4
	v_sub_u32_e32 v2, v2, v3
	s_ashr_i32 s11, s10, 8
	s_lshl_b32 s52, s36, 10
	v_and_or_b32 v4, v6, s4, v4
	v_lshrrev_b32_e32 v7, 2, v6
	v_lshlrev_b32_e32 v8, 1, v6
	v_lshlrev_b32_e32 v5, 5, v5
	v_ashrrev_i16_sdwa v2, v226, sext(v2) dst_sel:DWORD dst_unused:UNUSED_PAD src0_sel:DWORD src1_sel:BYTE_0
	v_readlane_b32 s4, v254, 56
	v_and_b32_e32 v7, 4, v7
	v_and_b32_e32 v8, 24, v8
	v_and_b32_e32 v5, 32, v5
	v_bfe_i32 v2, v2, 0, 16
	v_readlane_b32 s5, v254, 57
	s_add_u32 s54, s8, s4
	v_or3_b32 v4, v4, v7, v8
	v_add_lshl_u32 v2, v5, v2, 1
	s_addc_u32 s55, s9, s5
	s_add_i32 s71, s52, 0
	v_lshl_add_u32 v136, v4, 9, v2
	s_add_i32 m0, s71, 0x10000
	v_lshl_add_u32 v138, v6, 9, v2
	global_load_lds_dwordx4 v136, s[54:55]
	s_add_i32 m0, s71, 0x12000
	s_add_u32 s4, s54, 0x10000
	global_load_lds_dwordx4 v132, s[54:55]
	s_addc_u32 s5, s55, 0
	s_add_i32 m0, s71, 0x14000
	v_mov_b32_e32 v137, v99
	global_load_lds_dwordx4 v136, s[4:5]
	s_add_i32 m0, s71, 0x16000
	v_mov_b32_e32 v133, v99
	global_load_lds_dwordx4 v132, s[4:5]
	v_readlane_b32 s4, v254, 54
	v_readlane_b32 s5, v254, 55
	s_add_u32 s56, s6, s4
	s_addc_u32 s57, s7, s5
	s_add_i32 s72, s71, 0x2000
	s_mov_b32 m0, s71
	s_add_u32 s4, s56, 0x10000
	global_load_lds_dwordx4 v138, s[56:57]
	s_mov_b32 m0, s72
	s_addc_u32 s5, s57, 0
	s_add_i32 s73, s71, 0x4000
	global_load_lds_dwordx4 v134, s[56:57]
	s_mov_b32 m0, s73
	s_add_i32 s74, s71, 0x6000
	global_load_lds_dwordx4 v138, s[4:5]
	s_mov_b32 m0, s74
	v_mov_b32_e32 v139, v99
	global_load_lds_dwordx4 v134, s[4:5]
	v_mov_b32_e32 v135, v99
	s_cmp_eq_u32 s11, 1
	v_lshl_add_u64 v[8:9], s[54:55], 0, v[136:137]
	v_lshl_add_u64 v[6:7], s[54:55], 0, v[132:133]
	v_lshl_add_u64 v[2:3], s[56:57], 0, v[138:139]
	s_cselect_b64 s[4:5], -1, 0
	s_cmp_lg_u32 s11, 1
	v_lshl_add_u64 v[4:5], s[56:57], 0, v[134:135]
	s_cbranch_scc1 .LBB0_474
	s_barrier
